# attention K staging: lane^1/^2/^4 butterfly of the row sum of squares as DPP moves instead of ds_bpermute
# baseline (speedup 1.0000x reference)
; __device__ __forceinline__ void attn_unit(LAS unsigned char* lds, const bf16* P, bf16* Y, const float* gq, const float* gk, int b, int h, int qb, int tid, int wid, int lane, ...
;     ...
;             for (int hf = 0; hf < 2; ++hf) {
;                 float kf[8];
; #pragma unroll
;                 for (int i = 0; i < 4; ++i) { kf[2 * i] = blo(kw[hf][i]); kf[2 * i + 1] = bhi(kw[hf][i]); }
;                 float ss = 0.f;
; #pragma unroll
;                 for (int i = 0; i < 8; ++i) ss += kf[i] * kf[i];
;                 ss += __shfl_xor(ss, 1); ss += __shfl_xor(ss, 2); ss += __shfl_xor(ss, 4);
;                 const float rs = __builtin_amdgcn_rsqf(ss * (1.0f / 64.0f) + EPSN);
; #pragma unroll
;                 for (int i = 0; i < 4; ++i) { kf[i] *= rs * gk0[i]; kf[4 + i] *= rs * gk1[i]; }
;                 v4u o; o.x = pk2(kf[0], kf[1]); o.y = pk2(kf[2], kf[3]); o.z = pk2(kf[4], kf[5]); o.w = pk2(kf[6], kf[7]);
;                 *(LAS v4u*)(Ks + (sr + 64 * hf) * 72 + 8 * dc) = o;
; #pragma unroll
;                 for (int i = 0; i < 4; ++i) { Vt[(8 * (dcv + 4 * hf) + 2 * i) * 136 + srv] = (bf16)(vw[hf][i] & 0xffffu); Vt[(8 * (dcv + 4 * hf) + 2 * i + 1) * 136 + srv] = (bf16)(vw[hf][i] >> 16); }
;             }
;         }
;         if (tid == 0) flags[(it + 1) % 3] = 0;
;         LBAR();
;         if (!wdone) {
; #pragma unroll
;             for (int p = 3; p >= 0; --p) {
;                 if (8 * kt + 2 * p <= tg && !wdone) {
;                     float av[2][4];
; #pragma unroll
;                     for (int u = 1; u >= 0; --u) {
;                         const int st = 2 * p + u, sg = 8 * kt + st;
;                         if (sg > tg) {
; #pragma unroll
;                             for (int j = 0; j < 4; ++j) av[u][j] = 0.f;
;                         } else {
;                             const bf16x8 a0 = *(const LAS bf16x8*)(Ks + (16 * st + tq) * 72 + 8 * quad), a1 = *(const LAS bf16x8*)(Ks + (16 * st + tq) * 72 + 32 + 8 * quad);
;                             f32x4 z = (f32x4){0.f, 0.f, 0.f, 0.f};
;                             z = mfma16(a0, Bq0, z); z = mfma16(a1, Bq1, z);
;                             float r[4], be[4];
; #pragma unroll
;                             for (int j = 0; j < 4; ++j) { const float e = fexp2(fminf(z[j], 80.f)); const float rr = frcp(1.0f + e); r[j] = rr; be[j] = e * rr; }
;                             if (sg == tg) {
.LBB0_329:
	v_and_b32_e32 v70, 0xffff0000, v52
	v_lshlrev_b32_e32 v69, 16, v52
	v_mul_f32_e32 v75, v70, v70
	v_lshlrev_b32_e32 v71, 16, v53
	v_fmac_f32_e32 v75, v69, v69
	v_and_b32_e32 v72, 0xffff0000, v53
	v_fmac_f32_e32 v75, v71, v71
	v_lshlrev_b32_e32 v73, 16, v54
	v_fmac_f32_e32 v75, v72, v72
	v_and_b32_e32 v74, 0xffff0000, v54
	v_fmac_f32_e32 v75, v73, v73
	v_and_b32_e32 v52, 0xffff0000, v55
	v_lshlrev_b32_e32 v53, 16, v55
	v_fmac_f32_e32 v75, v74, v74
	v_pk_mul_f32 v[54:55], v[52:53], v[52:53]
	v_lshlrev_b32_e32 v80, 16, v50
	v_add_f32_e32 v55, v55, v75
	v_add_f32_e32 v54, v54, v55
	s_nop 1
	v_mov_b32_dpp v55, v54 quad_perm:[1,0,3,2] row_mask:0xf bank_mask:0xf
	v_and_b32_e32 v81, 0xffff0000, v50
	v_and_b32_e32 v79, 0xffff0000, v49
	s_waitcnt lgkmcnt(0)
	v_add_f32_e32 v54, v54, v55
	s_nop 1
	v_mov_b32_dpp v55, v54 quad_perm:[2,3,0,1] row_mask:0xf bank_mask:0xf
	s_waitcnt lgkmcnt(0)
	v_add_f32_e32 v54, v54, v55
	s_nop 1
	v_mov_b32_dpp v55, v54 row_half_mirror row_mask:0xf bank_mask:0xf
	s_waitcnt lgkmcnt(0)
	v_add_f32_e32 v54, v54, v55
	v_fmamk_f32 v54, v54, 0x3c800000, v139
	v_rsq_f32_e32 v75, v54
	s_waitcnt vmcnt(1)
	v_mul_f32_e32 v77, v33, v75
	s_waitcnt vmcnt(0)
	v_mul_f32_e32 v76, v37, v75
	v_mul_f32_e32 v74, v77, v74
	v_and_b32_e32 v77, 0xffff0000, v48
	v_mul_f32_e32 v78, v38, v75
	v_mul_f32_e32 v70, v76, v70
	v_lshlrev_b32_e32 v76, 16, v48
	v_mul_f32_e32 v50, v77, v77
	v_mul_f32_e32 v54, v36, v75
	v_mul_f32_e32 v71, v78, v71
	v_lshlrev_b32_e32 v78, 16, v49
	v_fmac_f32_e32 v50, v76, v76
	v_mul_f32_e32 v69, v54, v69
	v_mul_f32_e32 v54, v34, v75
	v_fmac_f32_e32 v50, v78, v78
	v_mul_f32_e32 v55, v32, v75
	v_mul_f32_e32 v53, v54, v53
	v_mul_f32_e32 v54, v39, v75
	v_fmac_f32_e32 v50, v79, v79
	v_mul_f32_e32 v73, v55, v73
	v_mul_f32_e32 v72, v54, v72
	v_fmac_f32_e32 v50, v80, v80
	v_and_b32_e32 v54, 0xffff0000, v51
	v_lshlrev_b32_e32 v55, 16, v51
	v_fmac_f32_e32 v50, v81, v81
	v_pk_mul_f32 v[48:49], v[54:55], v[54:55]
	s_nop 0
	v_add_f32_e32 v49, v49, v50
	v_add_f32_e32 v50, v48, v49
	s_nop 1
	v_mov_b32_dpp v51, v50 quad_perm:[1,0,3,2] row_mask:0xf bank_mask:0xf
	v_mul_f32_e32 v48, v35, v75
	v_mul_f32_e32 v52, v48, v52
	v_cvt_pk_bf16_f32 v48, v69, v70
	v_cvt_pk_bf16_f32 v49, v71, v72
	s_waitcnt lgkmcnt(0)
	v_add_f32_e32 v69, v50, v51
	s_nop 1
	v_mov_b32_dpp v70, v69 quad_perm:[2,3,0,1] row_mask:0xf bank_mask:0xf
	v_cvt_pk_bf16_f32 v50, v73, v74
	v_cvt_pk_bf16_f32 v51, v53, v52
	ds_write_b128 v142, v[48:51]
	ds_write_b16 v127, v44 offset:18432
	ds_write_b16_d16_hi v127, v44 offset:18704
	ds_write_b16 v127, v45 offset:18976
	ds_write_b16_d16_hi v127, v45 offset:19248
	ds_write_b16 v127, v46 offset:19520
	s_waitcnt lgkmcnt(6)
	v_add_f32_e32 v48, v69, v70
	s_nop 1
	v_mov_b32_dpp v49, v48 row_half_mirror row_mask:0xf bank_mask:0xf
	ds_write_b16_d16_hi v127, v46 offset:19792
	ds_write_b16 v127, v47 offset:20064
	ds_write_b16_d16_hi v127, v47 offset:20336
	s_waitcnt lgkmcnt(3)
	v_add_f32_e32 v44, v48, v49
	v_fmamk_f32 v44, v44, 0x3c800000, v139
	v_rsq_f32_e32 v44, v44
	s_nop 0
	v_mul_f32_e32 v45, v36, v44
	v_mul_f32_e32 v46, v32, v44
	v_mul_f32_e32 v47, v37, v44
	v_mul_f32_e32 v45, v45, v76
	v_mul_f32_e32 v46, v46, v80
	v_mul_f32_e32 v47, v47, v77
	v_mul_f32_e32 v48, v33, v44
	v_mul_f32_e32 v49, v38, v44
	v_mul_f32_e32 v50, v34, v44
	v_mul_f32_e32 v51, v39, v44
	v_mul_f32_e32 v44, v35, v44
	v_mul_f32_e32 v48, v48, v81
	v_mul_f32_e32 v49, v49, v78
	v_mul_f32_e32 v50, v50, v55
	v_mul_f32_e32 v51, v51, v79
	v_mul_f32_e32 v52, v44, v54
	v_cvt_pk_bf16_f32 v44, v45, v47
	v_cvt_pk_bf16_f32 v45, v49, v51
	v_cvt_pk_bf16_f32 v46, v46, v48
	v_cvt_pk_bf16_f32 v47, v50, v52
	ds_write_b128 v142, v[44:47] offset:9216
	ds_write_b16 v127, v40 offset:27136
	ds_write_b16_d16_hi v127, v40 offset:27408
	ds_write_b16 v127, v41 offset:27680
	ds_write_b16_d16_hi v127, v41 offset:27952
	ds_write_b16 v127, v42 offset:28224
	ds_write_b16_d16_hi v127, v42 offset:28496
	ds_write_b16 v127, v43 offset:28768
	ds_write_b16_d16_hi v127, v43 offset:29040
	s_mov_b64 s[10:11], exec
	v_readlane_b32 s12, v249, 28
	v_readlane_b32 s13, v249, 29
	s_and_b64 s[12:13], s[10:11], s[12:13]
	s_mov_b64 exec, s[12:13]
	ds_write_b32 v95, v95 offset:35844
	s_or_b64 exec, exec, s[10:11]
	s_waitcnt lgkmcnt(0)
	s_barrier
	s_andn2_b64 vcc, exec, s[0:1]
	s_cbranch_vccnz .LBB0_342
	s_andn2_b64 vcc, exec, s[18:19]
	s_cbranch_vccnz .LBB0_343
	ds_read_b128 v[40:43], v134
	ds_read_b128 v[44:47], v134 offset:64
	s_andn2_b64 vcc, exec, s[20:21]
	s_waitcnt lgkmcnt(1)
	v_mfma_f32_16x16x32_bf16 v[40:43], v[40:43], v[24:27], 0
	s_waitcnt lgkmcnt(0)
	v_mfma_f32_16x16x32_bf16 v[40:43], v[44:47], v[28:31], v[40:43]
	s_nop 7
	v_min_f32_e32 v40, 0x42a00000, v40
	v_min_f32_e32 v41, 0x42a00000, v41
	v_min_f32_e32 v42, 0x42a00000, v42
	v_min_f32_e32 v43, 0x42a00000, v43
	v_exp_f32_e32 v40, v40
	v_exp_f32_e32 v41, v41
	v_exp_f32_e32 v46, v42
	v_exp_f32_e32 v47, v43
	v_pk_add_f32 v[42:43], v[40:41], v[250:251]
	v_pk_add_f32 v[44:45], v[46:47], v[250:251]
	v_rcp_f32_e32 v48, v42
	v_rcp_f32_e32 v49, v43
	v_rcp_f32_e32 v44, v44
	v_rcp_f32_e32 v45, v45
	v_pk_mul_f32 v[42:43], v[40:41], v[48:49]
	v_pk_mul_f32 v[40:41], v[46:47], v[44:45]
	s_cbranch_vccnz .LBB0_335
	v_mov_b32_e32 v46, v93
	s_nop 0
	v_cmp_lt_i32_e64 s[12:13], v129, v46
	v_cmp_lt_i32_e64 s[14:15], v130, v46
	v_cmp_lt_i32_e64 s[10:11], v128, v46
	s_or_b64 s[12:13], s[14:15], s[12:13]
	v_cmp_lt_i32_e32 vcc, v98, v46
	s_or_b64 s[10:11], s[12:13], s[10:11]
	s_or_b64 vcc, s[10:11], vcc
	v_cndmask_b32_e64 v41, 0, v41, s[14:15]
	v_cndmask_b32_e64 v40, 0, v40, s[12:13]
	v_cndmask_b32_e64 v43, 0, v43, s[10:11]
	v_cndmask_b32_e32 v42, 0, v42, vcc
	v_cndmask_b32_e64 v44, 1.0, v44, s[12:13]
	v_cndmask_b32_e64 v49, 1.0, v49, s[10:11]
	v_cndmask_b32_e32 v48, 1.0, v48, vcc
	v_cndmask_b32_e64 v45, 1.0, v45, s[14:15]

; #define LAS __attribute__((address_space(3)))
; __device__ __forceinline__ unsigned pk2(float lo, float hi) { unsigned r; asm("v_cvt_pk_bf16_f32 %0, %1, %2" : "=v"(r) : "v"(lo), "v"(hi)); return r; }
; __device__ __forceinline__ float blo(unsigned w) { return __uint_as_float(w << 16); }
; __device__ __forceinline__ float bhi(unsigned w) { return __uint_as_float(w & 0xffff0000u); }
; __device__ __forceinline__ void attn_unit(LAS unsigned char* lds, const bf16* P, bf16* Y, const float* gq, const float* gk, int b, int h, int qb, int tid, int wid, int lane, ...
;     ...
;             for (int hf = 0; hf < 2; ++hf) {
;                 float kf[8];
; #pragma unroll
;                 for (int i = 0; i < 4; ++i) { kf[2 * i] = blo(kw[hf][i]); kf[2 * i + 1] = bhi(kw[hf][i]); }
;                 float ss = 0.f;
; #pragma unroll
;                 for (int i = 0; i < 8; ++i) ss += kf[i] * kf[i];
;                 ss += __shfl_xor(ss, 1); ss += __shfl_xor(ss, 2); ss += __shfl_xor(ss, 4);
;                 const float rs = __builtin_amdgcn_rsqf(ss * (1.0f / 64.0f) + EPSN);
; #pragma unroll
;                 for (int i = 0; i < 4; ++i) { kf[i] *= rs * gk0[i]; kf[4 + i] *= rs * gk1[i]; }
;                 v4u o; o.x = pk2(kf[0], kf[1]); o.y = pk2(kf[2], kf[3]); o.z = pk2(kf[4], kf[5]); o.w = pk2(kf[6], kf[7]);
;                 *(LAS v4u*)(Ks + (sr + 64 * hf) * 72 + 8 * dc) = o;
; #pragma unroll
;                 for (int i = 0; i < 4; ++i) { Vt[(8 * (dcv + 4 * hf) + 2 * i) * 136 + srv] = (bf16)(vw[hf][i] & 0xffffu); Vt[(8 * (dcv + 4 * hf) + 2 * i + 1) * 136 + srv] = (bf16)(vw[hf][i] >> 16); }
;             }
;         }
;         if (tid == 0) flags[(it + 1) % 3] = 0;
.LBB0_383:
	v_and_b32_e32 v143, 0xffff0000, v84
	v_lshlrev_b32_e32 v105, 16, v84
	v_mul_f32_e32 v148, v143, v143
	v_lshlrev_b32_e32 v144, 16, v85
	v_fmac_f32_e32 v148, v105, v105
	v_and_b32_e32 v145, 0xffff0000, v85
	v_fmac_f32_e32 v148, v144, v144
	v_lshlrev_b32_e32 v146, 16, v86
	v_fmac_f32_e32 v148, v145, v145
	v_and_b32_e32 v147, 0xffff0000, v86
	v_fmac_f32_e32 v148, v146, v146
	v_and_b32_e32 v84, 0xffff0000, v87
	v_lshlrev_b32_e32 v85, 16, v87
	v_fmac_f32_e32 v148, v147, v147
	v_pk_mul_f32 v[86:87], v[84:85], v[84:85]
	v_lshlrev_b32_e32 v153, 16, v66
	v_add_f32_e32 v87, v87, v148
	v_add_f32_e32 v86, v86, v87
	s_nop 1
	v_mov_b32_dpp v87, v86 quad_perm:[1,0,3,2] row_mask:0xf bank_mask:0xf
	v_and_b32_e32 v154, 0xffff0000, v66
	v_and_b32_e32 v152, 0xffff0000, v65
	s_waitcnt lgkmcnt(0)
	v_add_f32_e32 v86, v86, v87
	s_nop 1
	v_mov_b32_dpp v87, v86 quad_perm:[2,3,0,1] row_mask:0xf bank_mask:0xf
	s_waitcnt lgkmcnt(0)
	v_add_f32_e32 v86, v86, v87
	s_nop 1
	v_mov_b32_dpp v87, v86 row_half_mirror row_mask:0xf bank_mask:0xf
	s_waitcnt lgkmcnt(0)
	v_add_f32_e32 v86, v86, v87
	v_fmamk_f32 v86, v86, 0x3c800000, v139
	v_rsq_f32_e32 v148, v86
	s_nop 0
	v_mul_f32_e32 v150, v33, v148
	v_mul_f32_e32 v149, v37, v148
	v_mul_f32_e32 v147, v150, v147
	v_and_b32_e32 v150, 0xffff0000, v64
	v_mul_f32_e32 v151, v38, v148
	v_mul_f32_e32 v143, v149, v143
	v_lshlrev_b32_e32 v149, 16, v64
	v_mul_f32_e32 v66, v150, v150
	v_mul_f32_e32 v86, v36, v148
	v_mul_f32_e32 v144, v151, v144
	v_lshlrev_b32_e32 v151, 16, v65
	v_fmac_f32_e32 v66, v149, v149
	v_mul_f32_e32 v105, v86, v105
	v_mul_f32_e32 v86, v34, v148
	v_fmac_f32_e32 v66, v151, v151
	v_mul_f32_e32 v87, v32, v148
	v_mul_f32_e32 v85, v86, v85
	v_mul_f32_e32 v86, v39, v148
	v_fmac_f32_e32 v66, v152, v152
	v_mul_f32_e32 v146, v87, v146
	v_mul_f32_e32 v145, v86, v145
	v_fmac_f32_e32 v66, v153, v153
	v_and_b32_e32 v86, 0xffff0000, v67
	v_lshlrev_b32_e32 v87, 16, v67
	v_fmac_f32_e32 v66, v154, v154
	v_pk_mul_f32 v[64:65], v[86:87], v[86:87]
	s_nop 0
	v_add_f32_e32 v65, v65, v66
	v_add_f32_e32 v66, v64, v65
	s_nop 1
	v_mov_b32_dpp v67, v66 quad_perm:[1,0,3,2] row_mask:0xf bank_mask:0xf
	v_mul_f32_e32 v64, v35, v148
	v_mul_f32_e32 v84, v64, v84
	v_cvt_pk_bf16_f32 v64, v105, v143
	v_cvt_pk_bf16_f32 v65, v144, v145
	s_waitcnt lgkmcnt(0)
	v_add_f32_e32 v105, v66, v67
	s_nop 1
	v_mov_b32_dpp v143, v105 quad_perm:[2,3,0,1] row_mask:0xf bank_mask:0xf
	v_cvt_pk_bf16_f32 v66, v146, v147
	v_cvt_pk_bf16_f32 v67, v85, v84
	ds_write_b128 v142, v[64:67]
	ds_write_b16 v127, v60 offset:18432
	ds_write_b16_d16_hi v127, v60 offset:18704
	ds_write_b16 v127, v61 offset:18976
	ds_write_b16_d16_hi v127, v61 offset:19248
	ds_write_b16 v127, v62 offset:19520
	s_waitcnt lgkmcnt(6)
	v_add_f32_e32 v64, v105, v143
	s_nop 1
	v_mov_b32_dpp v65, v64 row_half_mirror row_mask:0xf bank_mask:0xf
	ds_write_b16_d16_hi v127, v62 offset:19792
	ds_write_b16 v127, v63 offset:20064
	ds_write_b16_d16_hi v127, v63 offset:20336
	s_waitcnt lgkmcnt(3)
	v_add_f32_e32 v60, v64, v65
	v_fmamk_f32 v60, v60, 0x3c800000, v139
	v_rsq_f32_e32 v60, v60
	s_nop 0
	v_mul_f32_e32 v61, v36, v60
	v_mul_f32_e32 v62, v32, v60
	v_mul_f32_e32 v63, v37, v60
	v_mul_f32_e32 v61, v61, v149
	v_mul_f32_e32 v62, v62, v153
	v_mul_f32_e32 v63, v63, v150
	v_mul_f32_e32 v64, v33, v60
	v_mul_f32_e32 v65, v38, v60
	v_mul_f32_e32 v66, v34, v60
	v_mul_f32_e32 v67, v39, v60
	v_mul_f32_e32 v60, v35, v60
	v_mul_f32_e32 v64, v64, v154
	v_mul_f32_e32 v65, v65, v151
	v_mul_f32_e32 v66, v66, v87
	v_mul_f32_e32 v67, v67, v152
	v_mul_f32_e32 v84, v60, v86
	v_cvt_pk_bf16_f32 v60, v61, v63
	v_cvt_pk_bf16_f32 v61, v65, v67
	v_cvt_pk_bf16_f32 v62, v62, v64
	v_cvt_pk_bf16_f32 v63, v66, v84
	ds_write_b128 v142, v[60:63] offset:9216
	ds_write_b16 v127, v56 offset:27136
	ds_write_b16_d16_hi v127, v56 offset:27408
	ds_write_b16 v127, v57 offset:27680
	ds_write_b16_d16_hi v127, v57 offset:27952
	ds_write_b16 v127, v58 offset:28224
	ds_write_b16_d16_hi v127, v58 offset:28496
	ds_write_b16 v127, v59 offset:28768
	ds_write_b16_d16_hi v127, v59 offset:29040
	s_mov_b64 s[12:13], exec
	v_readlane_b32 s14, v249, 28
	v_readlane_b32 s15, v249, 29
	s_and_b64 s[14:15], s[12:13], s[14:15]
	s_mov_b64 exec, s[14:15]
	s_cbranch_execz .LBB0_385
	s_mul_hi_u32 s14, s77, 0xaaaaaaab
	s_lshr_b32 s14, s14, 1
	s_mul_i32 s14, s14, -12
	s_add_i32 s14, s80, s14
	v_mov_b32_e32 v56, s14
	ds_write_b32 v56, v95

; __device__ __forceinline__ void attn_unit(LAS unsigned char* lds, const bf16* P, bf16* Y, const float* gq, const float* gk, int b, int h, int qb, int tid, int wid, int lane, ...
;     ...
;             for (int hf = 0; hf < 2; ++hf) {
;                 float kf[8];
; #pragma unroll
;                 for (int i = 0; i < 4; ++i) { kf[2 * i] = blo(kw[hf][i]); kf[2 * i + 1] = bhi(kw[hf][i]); }
;                 float ss = 0.f;
; #pragma unroll
;                 for (int i = 0; i < 8; ++i) ss += kf[i] * kf[i];
;                 ss += __shfl_xor(ss, 1); ss += __shfl_xor(ss, 2); ss += __shfl_xor(ss, 4);
;                 const float rs = __builtin_amdgcn_rsqf(ss * (1.0f / 64.0f) + EPSN);
; #pragma unroll
;                 for (int i = 0; i < 4; ++i) { kf[i] *= rs * gk0[i]; kf[4 + i] *= rs * gk1[i]; }
;                 v4u o; o.x = pk2(kf[0], kf[1]); o.y = pk2(kf[2], kf[3]); o.z = pk2(kf[4], kf[5]); o.w = pk2(kf[6], kf[7]);
;                 *(LAS v4u*)(Ks + (sr + 64 * hf) * 72 + 8 * dc) = o;
; #pragma unroll
;                 for (int i = 0; i < 4; ++i) { Vt[(8 * (dcv + 4 * hf) + 2 * i) * 136 + srv] = (bf16)(vw[hf][i] & 0xffffu); Vt[(8 * (dcv + 4 * hf) + 2 * i + 1) * 136 + srv] = (bf16)(vw[hf][i] >> 16); }
;             }
;         }
;         if (tid == 0) flags[(it + 1) % 3] = 0;
;         LBAR();
;         if (!wdone) {
; #pragma unroll
;             for (int p = 3; p >= 0; --p) {
;                 if (8 * kt + 2 * p <= tg && !wdone) {
;                     float av[2][4];
; #pragma unroll
;                     for (int u = 1; u >= 0; --u) {
;                         const int st = 2 * p + u, sg = 8 * kt + st;
;                         if (sg > tg) {
; #pragma unroll
;                             for (int j = 0; j < 4; ++j) av[u][j] = 0.f;
;                         } else {
;                             const bf16x8 a0 = *(const LAS bf16x8*)(Ks + (16 * st + tq) * 72 + 8 * quad), a1 = *(const LAS bf16x8*)(Ks + (16 * st + tq) * 72 + 32 + 8 * quad);
;                             f32x4 z = (f32x4){0.f, 0.f, 0.f, 0.f};
;                             z = mfma16(a0, Bq0, z); z = mfma16(a1, Bq1, z);
;                             float r[4], be[4];
; #pragma unroll
;                             for (int j = 0; j < 4; ++j) { const float e = fexp2(fminf(z[j], 80.f)); const float rr = frcp(1.0f + e); r[j] = rr; be[j] = e * rr; }
;                             if (sg == tg) {
.LBB0_853:
	v_and_b32_e32 v70, 0xffff0000, v52
	v_lshlrev_b32_e32 v69, 16, v52
	v_mul_f32_e32 v75, v70, v70
	v_lshlrev_b32_e32 v71, 16, v53
	v_fmac_f32_e32 v75, v69, v69
	v_and_b32_e32 v72, 0xffff0000, v53
	v_fmac_f32_e32 v75, v71, v71
	v_lshlrev_b32_e32 v73, 16, v54
	v_fmac_f32_e32 v75, v72, v72
	v_and_b32_e32 v74, 0xffff0000, v54
	v_fmac_f32_e32 v75, v73, v73
	v_and_b32_e32 v52, 0xffff0000, v55
	v_lshlrev_b32_e32 v53, 16, v55
	v_fmac_f32_e32 v75, v74, v74
	v_pk_mul_f32 v[54:55], v[52:53], v[52:53]
	v_lshlrev_b32_e32 v80, 16, v50
	v_add_f32_e32 v55, v55, v75
	v_add_f32_e32 v54, v54, v55
	s_nop 1
	v_mov_b32_dpp v55, v54 quad_perm:[1,0,3,2] row_mask:0xf bank_mask:0xf
	v_and_b32_e32 v81, 0xffff0000, v50
	v_and_b32_e32 v79, 0xffff0000, v49
	s_waitcnt lgkmcnt(0)
	v_add_f32_e32 v54, v54, v55
	s_nop 1
	v_mov_b32_dpp v55, v54 quad_perm:[2,3,0,1] row_mask:0xf bank_mask:0xf
	s_waitcnt lgkmcnt(0)
	v_add_f32_e32 v54, v54, v55
	s_nop 1
	v_mov_b32_dpp v55, v54 row_half_mirror row_mask:0xf bank_mask:0xf
	s_waitcnt lgkmcnt(0)
	v_add_f32_e32 v54, v54, v55
	v_fmamk_f32 v54, v54, 0x3c800000, v142
	v_rsq_f32_e32 v75, v54
	s_waitcnt vmcnt(1)
	v_mul_f32_e32 v77, v33, v75
	s_waitcnt vmcnt(0)
	v_mul_f32_e32 v76, v37, v75
	v_mul_f32_e32 v74, v77, v74
	v_and_b32_e32 v77, 0xffff0000, v48
	v_mul_f32_e32 v78, v38, v75
	v_mul_f32_e32 v70, v76, v70
	v_lshlrev_b32_e32 v76, 16, v48
	v_mul_f32_e32 v50, v77, v77
	v_mul_f32_e32 v54, v36, v75
	v_mul_f32_e32 v71, v78, v71
	v_lshlrev_b32_e32 v78, 16, v49
	v_fmac_f32_e32 v50, v76, v76
	v_mul_f32_e32 v69, v54, v69
	v_mul_f32_e32 v54, v34, v75
	v_fmac_f32_e32 v50, v78, v78
	v_mul_f32_e32 v55, v32, v75
	v_mul_f32_e32 v53, v54, v53
	v_mul_f32_e32 v54, v39, v75
	v_fmac_f32_e32 v50, v79, v79
	v_mul_f32_e32 v73, v55, v73
	v_mul_f32_e32 v72, v54, v72
	v_fmac_f32_e32 v50, v80, v80
	v_and_b32_e32 v54, 0xffff0000, v51
	v_lshlrev_b32_e32 v55, 16, v51
	v_fmac_f32_e32 v50, v81, v81
	v_pk_mul_f32 v[48:49], v[54:55], v[54:55]
	s_nop 0
	v_add_f32_e32 v49, v49, v50
	v_add_f32_e32 v50, v48, v49
	s_nop 1
	v_mov_b32_dpp v51, v50 quad_perm:[1,0,3,2] row_mask:0xf bank_mask:0xf
	v_mul_f32_e32 v48, v35, v75
	v_mul_f32_e32 v52, v48, v52
	v_cvt_pk_bf16_f32 v48, v69, v70
	v_cvt_pk_bf16_f32 v49, v71, v72
	s_waitcnt lgkmcnt(0)
	v_add_f32_e32 v69, v50, v51
	s_nop 1
	v_mov_b32_dpp v70, v69 quad_perm:[2,3,0,1] row_mask:0xf bank_mask:0xf
	v_cvt_pk_bf16_f32 v50, v73, v74
	v_cvt_pk_bf16_f32 v51, v53, v52
	ds_write_b128 v145, v[48:51]
	ds_write_b16 v129, v44 offset:18432
	ds_write_b16_d16_hi v129, v44 offset:18704
	ds_write_b16 v129, v45 offset:18976
	ds_write_b16_d16_hi v129, v45 offset:19248
	ds_write_b16 v129, v46 offset:19520
	s_waitcnt lgkmcnt(6)
	v_add_f32_e32 v48, v69, v70
	s_nop 1
	v_mov_b32_dpp v49, v48 row_half_mirror row_mask:0xf bank_mask:0xf
	ds_write_b16_d16_hi v129, v46 offset:19792
	ds_write_b16 v129, v47 offset:20064
	ds_write_b16_d16_hi v129, v47 offset:20336
	s_waitcnt lgkmcnt(3)
	v_add_f32_e32 v44, v48, v49
	v_fmamk_f32 v44, v44, 0x3c800000, v142
	v_rsq_f32_e32 v44, v44
	s_nop 0
	v_mul_f32_e32 v45, v36, v44
	v_mul_f32_e32 v46, v32, v44
	v_mul_f32_e32 v47, v37, v44
	v_mul_f32_e32 v45, v45, v76
	v_mul_f32_e32 v46, v46, v80
	v_mul_f32_e32 v47, v47, v77
	v_mul_f32_e32 v48, v33, v44
	v_mul_f32_e32 v49, v38, v44
	v_mul_f32_e32 v50, v34, v44
	v_mul_f32_e32 v51, v39, v44
	v_mul_f32_e32 v44, v35, v44
	v_mul_f32_e32 v48, v48, v81
	v_mul_f32_e32 v49, v49, v78
	v_mul_f32_e32 v50, v50, v55
	v_mul_f32_e32 v51, v51, v79
	v_mul_f32_e32 v52, v44, v54
	v_cvt_pk_bf16_f32 v44, v45, v47
	v_cvt_pk_bf16_f32 v45, v49, v51
	v_cvt_pk_bf16_f32 v46, v46, v48
	v_cvt_pk_bf16_f32 v47, v50, v52
	ds_write_b128 v145, v[44:47] offset:9216
	ds_write_b16 v129, v40 offset:27136
	ds_write_b16_d16_hi v129, v40 offset:27408
	ds_write_b16 v129, v41 offset:27680
	ds_write_b16_d16_hi v129, v41 offset:27952
	ds_write_b16 v129, v42 offset:28224
	ds_write_b16_d16_hi v129, v42 offset:28496
	ds_write_b16 v129, v43 offset:28768
	ds_write_b16_d16_hi v129, v43 offset:29040
	s_mov_b64 s[10:11], exec
	v_readlane_b32 s12, v249, 8
	v_readlane_b32 s13, v249, 9
	s_and_b64 s[12:13], s[10:11], s[12:13]
	s_mov_b64 exec, s[12:13]
	ds_write_b32 v95, v95 offset:35844
	s_or_b64 exec, exec, s[10:11]
	s_waitcnt lgkmcnt(0)
	s_barrier
	s_andn2_b64 vcc, exec, s[0:1]
	s_cbranch_vccnz .LBB0_866
	s_andn2_b64 vcc, exec, s[18:19]
	s_cbranch_vccnz .LBB0_867
	ds_read_b128 v[40:43], v137
	ds_read_b128 v[44:47], v137 offset:64
	s_andn2_b64 vcc, exec, s[20:21]
	s_waitcnt lgkmcnt(1)
	v_mfma_f32_16x16x32_bf16 v[40:43], v[40:43], v[24:27], 0
	s_waitcnt lgkmcnt(0)
	v_mfma_f32_16x16x32_bf16 v[40:43], v[44:47], v[28:31], v[40:43]
	s_nop 7
	v_min_f32_e32 v40, 0x42a00000, v40
	v_min_f32_e32 v41, 0x42a00000, v41
	v_min_f32_e32 v42, 0x42a00000, v42
	v_min_f32_e32 v43, 0x42a00000, v43
	v_exp_f32_e32 v40, v40
	v_exp_f32_e32 v41, v41
	v_exp_f32_e32 v46, v42
	v_exp_f32_e32 v47, v43
	v_pk_add_f32 v[42:43], v[40:41], v[250:251]
	v_pk_add_f32 v[44:45], v[46:47], v[250:251]
	v_rcp_f32_e32 v48, v42
	v_rcp_f32_e32 v49, v43
	v_rcp_f32_e32 v44, v44
	v_rcp_f32_e32 v45, v45
	v_pk_mul_f32 v[42:43], v[40:41], v[48:49]
	v_pk_mul_f32 v[40:41], v[46:47], v[44:45]
	s_cbranch_vccnz .LBB0_859
	v_mov_b32_e32 v46, v91
	s_nop 0
	v_cmp_lt_i32_e64 s[12:13], v131, v46
	v_cmp_lt_i32_e64 s[14:15], v132, v46
	v_cmp_lt_i32_e64 s[10:11], v130, v46
	s_or_b64 s[12:13], s[14:15], s[12:13]
	v_cmp_lt_i32_e32 vcc, v98, v46
	s_or_b64 s[10:11], s[12:13], s[10:11]
	s_or_b64 vcc, s[10:11], vcc
	v_cndmask_b32_e64 v41, 0, v41, s[14:15]
	v_cndmask_b32_e64 v40, 0, v40, s[12:13]
	v_cndmask_b32_e64 v43, 0, v43, s[10:11]
	v_cndmask_b32_e32 v42, 0, v42, vcc
	v_cndmask_b32_e64 v44, 1.0, v44, s[12:13]
	v_cndmask_b32_e64 v49, 1.0, v49, s[10:11]
	v_cndmask_b32_e32 v48, 1.0, v48, vcc
	v_cndmask_b32_e64 v45, 1.0, v45, s[14:15]

; #define LAS __attribute__((address_space(3)))
; __device__ __forceinline__ unsigned pk2(float lo, float hi) { unsigned r; asm("v_cvt_pk_bf16_f32 %0, %1, %2" : "=v"(r) : "v"(lo), "v"(hi)); return r; }
; __device__ __forceinline__ float blo(unsigned w) { return __uint_as_float(w << 16); }
; __device__ __forceinline__ float bhi(unsigned w) { return __uint_as_float(w & 0xffff0000u); }
; __device__ __forceinline__ void attn_unit(LAS unsigned char* lds, const bf16* P, bf16* Y, const float* gq, const float* gk, int b, int h, int qb, int tid, int wid, int lane, ...
;     ...
;             for (int hf = 0; hf < 2; ++hf) {
;                 float kf[8];
; #pragma unroll
;                 for (int i = 0; i < 4; ++i) { kf[2 * i] = blo(kw[hf][i]); kf[2 * i + 1] = bhi(kw[hf][i]); }
;                 float ss = 0.f;
; #pragma unroll
;                 for (int i = 0; i < 8; ++i) ss += kf[i] * kf[i];
;                 ss += __shfl_xor(ss, 1); ss += __shfl_xor(ss, 2); ss += __shfl_xor(ss, 4);
;                 const float rs = __builtin_amdgcn_rsqf(ss * (1.0f / 64.0f) + EPSN);
; #pragma unroll
;                 for (int i = 0; i < 4; ++i) { kf[i] *= rs * gk0[i]; kf[4 + i] *= rs * gk1[i]; }
;                 v4u o; o.x = pk2(kf[0], kf[1]); o.y = pk2(kf[2], kf[3]); o.z = pk2(kf[4], kf[5]); o.w = pk2(kf[6], kf[7]);
;                 *(LAS v4u*)(Ks + (sr + 64 * hf) * 72 + 8 * dc) = o;
; #pragma unroll
;                 for (int i = 0; i < 4; ++i) { Vt[(8 * (dcv + 4 * hf) + 2 * i) * 136 + srv] = (bf16)(vw[hf][i] & 0xffffu); Vt[(8 * (dcv + 4 * hf) + 2 * i + 1) * 136 + srv] = (bf16)(vw[hf][i] >> 16); }
;             }
;         }
;         if (tid == 0) flags[(it + 1) % 3] = 0;
.LBB0_907:
	v_and_b32_e32 v146, 0xffff0000, v84
	v_lshlrev_b32_e32 v105, 16, v84
	v_mul_f32_e32 v151, v146, v146
	v_lshlrev_b32_e32 v147, 16, v85
	v_fmac_f32_e32 v151, v105, v105
	v_and_b32_e32 v148, 0xffff0000, v85
	v_fmac_f32_e32 v151, v147, v147
	v_lshlrev_b32_e32 v149, 16, v86
	v_fmac_f32_e32 v151, v148, v148
	v_and_b32_e32 v150, 0xffff0000, v86
	v_fmac_f32_e32 v151, v149, v149
	v_and_b32_e32 v84, 0xffff0000, v87
	v_lshlrev_b32_e32 v85, 16, v87
	v_fmac_f32_e32 v151, v150, v150
	v_pk_mul_f32 v[86:87], v[84:85], v[84:85]
	v_lshlrev_b32_e32 v156, 16, v66
	v_add_f32_e32 v87, v87, v151
	v_add_f32_e32 v86, v86, v87
	s_nop 1
	v_mov_b32_dpp v87, v86 quad_perm:[1,0,3,2] row_mask:0xf bank_mask:0xf
	v_and_b32_e32 v157, 0xffff0000, v66
	v_and_b32_e32 v155, 0xffff0000, v65
	s_waitcnt lgkmcnt(0)
	v_add_f32_e32 v86, v86, v87
	s_nop 1
	v_mov_b32_dpp v87, v86 quad_perm:[2,3,0,1] row_mask:0xf bank_mask:0xf
	s_waitcnt lgkmcnt(0)
	v_add_f32_e32 v86, v86, v87
	s_nop 1
	v_mov_b32_dpp v87, v86 row_half_mirror row_mask:0xf bank_mask:0xf
	s_waitcnt lgkmcnt(0)
	v_add_f32_e32 v86, v86, v87
	v_fmamk_f32 v86, v86, 0x3c800000, v142
	v_rsq_f32_e32 v151, v86
	s_nop 0
	v_mul_f32_e32 v153, v33, v151
	v_mul_f32_e32 v152, v37, v151
	v_mul_f32_e32 v150, v153, v150
	v_and_b32_e32 v153, 0xffff0000, v64
	v_mul_f32_e32 v154, v38, v151
	v_mul_f32_e32 v146, v152, v146
	v_lshlrev_b32_e32 v152, 16, v64
	v_mul_f32_e32 v66, v153, v153
	v_mul_f32_e32 v86, v36, v151
	v_mul_f32_e32 v147, v154, v147
	v_lshlrev_b32_e32 v154, 16, v65
	v_fmac_f32_e32 v66, v152, v152
	v_mul_f32_e32 v105, v86, v105
	v_mul_f32_e32 v86, v34, v151
	v_fmac_f32_e32 v66, v154, v154
	v_mul_f32_e32 v87, v32, v151
	v_mul_f32_e32 v85, v86, v85
	v_mul_f32_e32 v86, v39, v151
	v_fmac_f32_e32 v66, v155, v155
	v_mul_f32_e32 v149, v87, v149
	v_mul_f32_e32 v148, v86, v148
	v_fmac_f32_e32 v66, v156, v156
	v_and_b32_e32 v86, 0xffff0000, v67
	v_lshlrev_b32_e32 v87, 16, v67
	v_fmac_f32_e32 v66, v157, v157
	v_pk_mul_f32 v[64:65], v[86:87], v[86:87]
	s_nop 0
	v_add_f32_e32 v65, v65, v66
	v_add_f32_e32 v66, v64, v65
	s_nop 1
	v_mov_b32_dpp v67, v66 quad_perm:[1,0,3,2] row_mask:0xf bank_mask:0xf
	v_mul_f32_e32 v64, v35, v151
	v_mul_f32_e32 v84, v64, v84
	v_cvt_pk_bf16_f32 v64, v105, v146
	v_cvt_pk_bf16_f32 v65, v147, v148
	s_waitcnt lgkmcnt(0)
	v_add_f32_e32 v105, v66, v67
	s_nop 1
	v_mov_b32_dpp v146, v105 quad_perm:[2,3,0,1] row_mask:0xf bank_mask:0xf
	v_cvt_pk_bf16_f32 v66, v149, v150
	v_cvt_pk_bf16_f32 v67, v85, v84
	ds_write_b128 v145, v[64:67]
	ds_write_b16 v129, v60 offset:18432
	ds_write_b16_d16_hi v129, v60 offset:18704
	ds_write_b16 v129, v61 offset:18976
	ds_write_b16_d16_hi v129, v61 offset:19248
	ds_write_b16 v129, v62 offset:19520
	s_waitcnt lgkmcnt(6)
	v_add_f32_e32 v64, v105, v146
	s_nop 1
	v_mov_b32_dpp v65, v64 row_half_mirror row_mask:0xf bank_mask:0xf
	ds_write_b16_d16_hi v129, v62 offset:19792
	ds_write_b16 v129, v63 offset:20064
	ds_write_b16_d16_hi v129, v63 offset:20336
	s_waitcnt lgkmcnt(3)
	v_add_f32_e32 v60, v64, v65
	v_fmamk_f32 v60, v60, 0x3c800000, v142
	v_rsq_f32_e32 v60, v60
	s_nop 0
	v_mul_f32_e32 v61, v36, v60
	v_mul_f32_e32 v62, v32, v60
	v_mul_f32_e32 v63, v37, v60
	v_mul_f32_e32 v61, v61, v152
	v_mul_f32_e32 v62, v62, v156
	v_mul_f32_e32 v63, v63, v153
	v_mul_f32_e32 v64, v33, v60
	v_mul_f32_e32 v65, v38, v60
	v_mul_f32_e32 v66, v34, v60
	v_mul_f32_e32 v67, v39, v60
	v_mul_f32_e32 v60, v35, v60
	v_mul_f32_e32 v64, v64, v157
	v_mul_f32_e32 v65, v65, v154
	v_mul_f32_e32 v66, v66, v87
	v_mul_f32_e32 v67, v67, v155
	v_mul_f32_e32 v84, v60, v86
	v_cvt_pk_bf16_f32 v60, v61, v63
	v_cvt_pk_bf16_f32 v61, v65, v67
	v_cvt_pk_bf16_f32 v62, v62, v64
	v_cvt_pk_bf16_f32 v63, v66, v84
	ds_write_b128 v145, v[60:63] offset:9216
	ds_write_b16 v129, v56 offset:27136
	ds_write_b16_d16_hi v129, v56 offset:27408
	ds_write_b16 v129, v57 offset:27680
	ds_write_b16_d16_hi v129, v57 offset:27952
	ds_write_b16 v129, v58 offset:28224
	ds_write_b16_d16_hi v129, v58 offset:28496
	ds_write_b16 v129, v59 offset:28768
	ds_write_b16_d16_hi v129, v59 offset:29040
	s_mov_b64 s[12:13], exec
	v_readlane_b32 s14, v249, 8
	v_readlane_b32 s15, v249, 9
	s_and_b64 s[14:15], s[12:13], s[14:15]
	s_mov_b64 exec, s[14:15]
	s_cbranch_execz .LBB0_909
	s_mul_hi_u32 s14, s75, 0xaaaaaaab
	s_lshr_b32 s14, s14, 1
	s_mul_i32 s14, s14, -12
	s_add_i32 s14, s78, s14
	v_mov_b32_e32 v56, s14
	ds_write_b32 v56, v95
